# k24: scan chunk loader (11 LDS-DMA per step) moved from the state-chain wave 2 to the light triangular-inverse wave 1 from step 1 on (address bases handed over through spare LDS)
# baseline (speedup 1.0000x reference)
.LBB0_812:
	s_and_b64 vcc, exec, s[46:47]
	s_cbranch_vccz .LBB0_841
	v_and_b32_e32 v0, 31, v128
	v_lshrrev_b32_e32 v1, 5, v148
	s_cmp_lt_u32 s61, 64
	v_mul_u32_u24_e32 v76, 0x90, v0
	v_lshlrev_b32_e32 v77, 3, v1
	v_mul_u32_u24_e32 v78, 24, v0
	v_and_b32_e32 v79, 32, v128
	v_lshlrev_b32_e32 v81, 9, v1
	s_mov_b64 s[4:5], -1
	v_lshlrev_b32_e32 v80, 5, v0
	v_lshlrev_b32_e32 v82, 2, v0
	s_cbranch_scc1 .LBB0_831
	s_add_i32 s4, 0, 0x17c00
	s_lshl_b32 s12, s42, 6
	s_lshl_b32 s10, s42, 4
	v_add3_u32 v83, s4, v81, v82
	s_lshl_b64 s[4:5], s[0:1], 21
	v_lshlrev_b32_e32 v0, 4, v148
	v_mov_b32_e32 v8, 0
	s_add_u32 s4, s92, s4
	v_and_b32_e32 v2, 48, v0
	v_lshlrev_b32_e32 v0, 8, v148
	v_mov_b32_e32 v1, v8
	s_addc_u32 s5, s93, s5
	v_lshl_add_u64 v[68:69], s[4:5], 0, v[0:1]
	s_lshl_b64 s[4:5], s[0:1], 23
	v_and_b32_e32 v1, 0x3c00, v0
	v_or_b32_e32 v1, s4, v1
	v_or3_b32 v2, v1, s12, v2
	s_lshl_b64 s[0:1], s[0:1], 24
	v_and_b32_e32 v0, 0x3800, v0
	v_and_b32_e32 v1, 7, v128
	v_mov_b32_e32 v3, s5
	v_or_b32_e32 v0, s0, v0
	s_lshl_b32 s0, s42, 7
	v_lshlrev_b32_e32 v1, 4, v1
	v_readlane_b32 s12, v254, 0
	v_lshl_add_u64 v[2:3], s[92:93], 0, v[2:3]
	s_mov_b64 s[4:5], 0x17b10000
	v_or3_b32 v0, v0, s0, v1
	v_mov_b32_e32 v1, s1
	v_readlane_b32 s18, v254, 6
	v_readlane_b32 s19, v254, 7
	v_mov_b32_e32 v14, v8
	v_mov_b32_e32 v15, v8
	v_lshl_add_u64 v[70:71], v[2:3], 0, s[4:5]
	v_lshl_add_u64 v[72:73], s[92:93], 0, v[0:1]
	v_readlane_b32 s13, v254, 1
	v_readlane_b32 s14, v254, 2
	v_readlane_b32 s15, v254, 3
	v_readlane_b32 s16, v254, 4
	v_readlane_b32 s17, v254, 5
	v_lshl_add_u64 v[74:75], s[18:19], 0, v[0:1]
	v_mov_b32_e32 v0, v8
	v_mov_b32_e32 v1, v8
	v_mov_b32_e32 v2, v8
	v_mov_b32_e32 v3, v8
	v_mov_b32_e32 v4, v8
	v_mov_b32_e32 v5, v8
	v_mov_b32_e32 v6, v8
	v_mov_b32_e32 v7, v8
	v_mov_b32_e32 v9, v8
	v_mov_b32_e32 v10, v8
	v_mov_b32_e32 v11, v8
	v_mov_b32_e32 v12, v8
	v_mov_b32_e32 v13, v8
	v_mov_b64_e32 v[30:31], v[14:15]
	v_mov_b64_e32 v[46:47], v[14:15]
	v_cmp_gt_u32_e64 s[6:7], 32, v148
	s_mov_b32 s33, 4
	v_cmp_gt_u32_e64 s[8:9], 16, v148
	s_mov_b32 s11, 0
	s_mov_b64 s[0:1], 0x2204000
	s_mov_b64 s[12:13], 0
	s_mov_b64 s[14:15], 0x37f20000
	s_mov_b64 s[16:17], 0x37f24000
	s_mov_b64 s[18:19], 0x20000
	s_mov_b64 s[20:21], 0x24000
	s_mov_b64 s[22:23], 0x8020000
	s_mov_b64 s[24:25], 0x8024000
	s_mov_b64 s[26:27], 0xfa20000
	s_mov_b64 s[28:29], 0xfa24000
	s_mov_b64 s[30:31], 0x2000
	s_mov_b64 s[34:35], 0x4000
	v_mov_b64_e32 v[28:29], v[12:13]
	v_mov_b64_e32 v[26:27], v[10:11]
	v_mov_b64_e32 v[24:25], v[8:9]
	v_mov_b64_e32 v[22:23], v[6:7]
	v_mov_b64_e32 v[20:21], v[4:5]
	v_mov_b64_e32 v[18:19], v[2:3]
	v_mov_b64_e32 v[16:17], v[0:1]
	v_mov_b64_e32 v[44:45], v[12:13]
	v_mov_b64_e32 v[42:43], v[10:11]
	v_mov_b64_e32 v[40:41], v[8:9]
	v_mov_b64_e32 v[38:39], v[6:7]
	v_mov_b64_e32 v[36:37], v[4:5]
	v_mov_b64_e32 v[34:35], v[2:3]
	v_mov_b64_e32 v[32:33], v[0:1]
	v_readfirstlane_b32 s64, v72
	v_readfirstlane_b32 s65, v73
	v_readfirstlane_b32 s66, v74
	v_readfirstlane_b32 s67, v75
	v_readfirstlane_b32 s68, v70
	v_readfirstlane_b32 s69, v71
	v_readfirstlane_b32 s70, v68
	v_readfirstlane_b32 s71, v69
	s_nop 1
	v_subrev_u32_e32 v102, s64, v72
	v_subrev_u32_e32 v103, s66, v74
	v_subrev_u32_e32 v104, s68, v70
	v_subrev_u32_e32 v105, s70, v68
	v_mov_b32_e32 v106, 0
	v_writelane_b32 v106, s64, 0
	v_writelane_b32 v106, s65, 1
	v_writelane_b32 v106, s66, 2
	v_writelane_b32 v106, s67, 3
	v_writelane_b32 v106, s68, 4
	v_writelane_b32 v106, s69, 5
	v_writelane_b32 v106, s70, 6
	v_writelane_b32 v106, s71, 7
	v_writelane_b32 v106, s10, 8
	s_mov_b32 s72, 0x26a00
	v_lshl_add_u32 v107, v148, 2, s72
	ds_write_b32 v107, v102
	ds_write_b32 v107, v103 offset:256
	ds_write_b32 v107, v104 offset:512
	ds_write_b32 v107, v105 offset:768
	ds_write_b32 v107, v106 offset:1024
	s_branch .LBB0_817

.LBB0_821:
	s_andn2_b64 vcc, exec, s[4:5]
	s_cbranch_vccz .LBB0_824
	s_cmpk_gt_u32 s38, 0
	s_mov_b64 s[4:5], -1
	s_cbranch_scc1 .LBB0_825

.LBB0_824:
	s_add_i32 s4, s33, -7
	s_and_b32 s4, s4, 3
	s_mulk_i32 s4, 0x5f00
	s_add_i32 s4, s4, 0
	v_lshlrev_b32_e32 v0, 1, v78
	v_lshlrev_b32_e32 v4, 1, v77
	v_add3_u32 v14, s4, v0, v4
	ds_read_b128 v[0:3], v14 offset:19968
	ds_read_b128 v[64:67], v14 offset:15872
	v_add3_u32 v9, s4, v76, v4
	v_cvt_pk_bf16_f32 v4, v16, v17
	s_waitcnt lgkmcnt(0)
	v_mfma_f32_32x32x16_bf16 v[48:63], v[0:3], v[64:67], 0
	ds_read_b128 v[0:3], v9
	ds_read_b128 v[10:13], v9 offset:64
	v_cvt_pk_bf16_f32 v5, v18, v19
	v_cvt_pk_bf16_f32 v6, v20, v21
	v_cvt_pk_bf16_f32 v7, v22, v23
	v_add_u32_e32 v100, v14, v80
	ds_read_b128 v[88:91], v9 offset:96
	s_waitcnt lgkmcnt(2)
	v_mfma_f32_32x32x16_bf16 v[48:63], v[0:3], v[4:7], v[48:63]
	ds_read_b128 v[0:3], v9 offset:32
	v_cvt_pk_bf16_f32 v4, v24, v25
	v_cvt_pk_bf16_f32 v5, v26, v27
	v_cvt_pk_bf16_f32 v6, v28, v29
	v_cvt_pk_bf16_f32 v7, v30, v31
	ds_read_b128 v[84:87], v100 offset:17440
	v_lshl_add_u32 v101, v79, 2, s4
	s_waitcnt lgkmcnt(1)
	v_mfma_f32_32x32x16_bf16 v[48:63], v[0:3], v[4:7], v[48:63]
	v_cvt_pk_bf16_f32 v0, v32, v33
	v_cvt_pk_bf16_f32 v1, v34, v35
	v_cvt_pk_bf16_f32 v2, v36, v37
	v_cvt_pk_bf16_f32 v3, v38, v39
	v_cvt_pk_bf16_f32 v4, v40, v41
	v_cvt_pk_bf16_f32 v5, v42, v43
	v_cvt_pk_bf16_f32 v6, v44, v45
	v_mfma_f32_32x32x16_bf16 v[48:63], v[10:13], v[0:3], v[48:63]
	v_cvt_pk_bf16_f32 v7, v46, v47
	ds_read_b128 v[92:95], v14 offset:21504
	ds_read_b128 v[96:99], v101 offset:24064
	v_mov_b32_e32 v14, v8
	v_mov_b32_e32 v15, v8
	v_mov_b32_e32 v9, v8
	v_mov_b32_e32 v10, v8
	v_mov_b32_e32 v11, v8
	v_mfma_f32_32x32x16_bf16 v[48:63], v[88:91], v[4:7], v[48:63]
	ds_read_b128 v[88:91], v100 offset:17408
	v_mov_b32_e32 v12, v8
	v_mov_b32_e32 v13, v8
	s_add_i32 s5, s0, 0xfddf9000
	s_and_b32 s5, s5, 0x1000
	s_waitcnt lgkmcnt(1)
	v_pk_mul_f32 v[18:19], v[18:19], v[98:99]
	v_pk_mul_f32 v[16:17], v[16:17], v[96:97]
	s_nop 3
	v_cvt_pk_bf16_f32 v48, v48, v49
	v_cvt_pk_bf16_f32 v49, v50, v51
	v_cvt_pk_bf16_f32 v50, v52, v53
	v_cvt_pk_bf16_f32 v51, v54, v55
	v_mov_b32_e32 v0, v56
	v_mov_b32_e32 v1, v57
	v_mov_b32_e32 v2, v58
	v_mov_b32_e32 v3, v59
	v_mov_b32_e32 v4, v60
	v_mov_b32_e32 v5, v61
	v_mov_b32_e32 v6, v62
	v_mov_b32_e32 v7, v63
	v_mfma_f32_32x32x16_bf16 v[48:63], v[92:95], v[48:51], 0
	s_nop 11
	v_cvt_pk_bf16_f32 v92, v48, v49
	v_cvt_pk_bf16_f32 v93, v50, v51
	v_cvt_pk_bf16_f32 v94, v52, v53
	v_cvt_pk_bf16_f32 v95, v54, v55
	v_mov_b64_e32 v[62:63], v[14:15]
	v_mov_b64_e32 v[60:61], v[12:13]
	v_mov_b64_e32 v[58:59], v[10:11]
	v_mov_b64_e32 v[56:57], v[8:9]
	v_mov_b64_e32 v[54:55], v[6:7]
	v_mov_b64_e32 v[52:53], v[4:5]
	v_mov_b64_e32 v[50:51], v[2:3]
	v_mov_b64_e32 v[48:49], v[0:1]
	v_add_u32_e32 v0, s5, v83
	v_add_u32_e32 v9, 0x800, v0
	s_waitcnt lgkmcnt(0)
	v_mfma_f32_32x32x16_bf16 v[48:63], v[88:91], v[92:95], v[48:63]
	v_add_u32_e32 v14, 0xc00, v0
	ds_read_b128 v[0:3], v101 offset:24080
	ds_read_b128 v[4:7], v101 offset:24096
	ds_read_b128 v[10:13], v101 offset:24112
	ds_read_b128 v[88:91], v101 offset:24176
	s_waitcnt lgkmcnt(3)
	v_pk_mul_f32 v[20:21], v[20:21], v[0:1]
	s_waitcnt lgkmcnt(2)
	v_pk_mul_f32 v[24:25], v[24:25], v[4:5]
	s_waitcnt lgkmcnt(1)
	v_pk_mul_f32 v[28:29], v[28:29], v[10:11]
	v_pk_mul_f32 v[30:31], v[30:31], v[12:13]
	v_mfma_f32_32x32x16_bf16 v[48:63], v[84:87], v[64:67], v[48:63]
	s_nop 11
	ds_write2_b32 v9, v48, v49 offset1:32
	ds_write2_b32 v9, v50, v51 offset0:64 offset1:96
	ds_write2_b32 v14, v52, v53 offset1:32
	ds_write2_b32 v14, v54, v55 offset0:64 offset1:96
	ds_read_b128 v[48:51], v100 offset:9216
	v_pk_mul_f32 v[26:27], v[26:27], v[6:7]
	v_pk_mul_f32 v[22:23], v[22:23], v[2:3]
	ds_read_b128 v[0:3], v100 offset:9248
	s_waitcnt lgkmcnt(6)
	v_pk_mul_f32 v[44:45], v[44:45], v[88:89]
	s_waitcnt lgkmcnt(1)
	v_mfma_f32_32x32x16_bf16 v[16:31], v[48:51], v[92:95], v[16:31]
	ds_read_b128 v[4:7], v101 offset:24160
	ds_read_b128 v[10:13], v101 offset:24128
	ds_read_b128 v[48:51], v101 offset:24144
	ds_read_b128 v[52:55], v100 offset:11776
	v_mul_f32_e64 v46, v46, v90
	v_mul_f32_e64 v47, v47, v91
	s_waitcnt lgkmcnt(3)
	v_pk_mul_f32 v[40:41], v[40:41], v[4:5]
	v_pk_mul_f32 v[42:43], v[42:43], v[6:7]
	s_waitcnt lgkmcnt(1)
	v_pk_mul_f32 v[36:37], v[36:37], v[48:49]
	v_pk_mul_f32 v[38:39], v[38:39], v[50:51]
	v_mfma_f32_32x32x16_bf16 v[16:31], v[0:3], v[64:67], v[16:31]
	v_mul_f32_e64 v34, v34, v12
	v_mul_f32_e64 v35, v35, v13
	v_mul_f32_e64 v32, v32, v10
	v_mul_f32_e64 v33, v33, v11
	ds_read_b128 v[0:3], v100 offset:11808
	s_waitcnt lgkmcnt(1)
	v_mfma_f32_32x32x16_bf16 v[32:47], v[52:55], v[92:95], v[32:47]
	s_waitcnt lgkmcnt(0)
	v_mfma_f32_32x32x16_bf16 v[32:47], v[0:3], v[64:67], v[32:47]
	s_cmpk_gt_u32 s38, 0
	s_mov_b64 s[4:5], -1
	s_cbranch_scc0 .LBB0_823

.LBB0_844:
	s_cmpk_gt_i32 s4, 0x1f9
	s_cbranch_scc1 .Linv_drain
	s_waitcnt vmcnt(22)
	s_branch .Linv_bar
.Linv_drain:
	s_waitcnt vmcnt(0)
.Linv_bar:
	s_waitcnt lgkmcnt(0)
	s_barrier
	s_add_i32 s4, s4, 1
	s_cmpk_eq_i32 s4, 0x202
	s_cbranch_scc1 .LBB0_849
.LBB0_845:
	s_cmp_lt_i32 s4, -1
	s_cbranch_scc1 .Linv_dma_skip
	s_cmpk_gt_i32 s4, 0x1f9
	s_cbranch_scc1 .Linv_dma_skip
	s_cmp_lg_u32 s4, -1
	s_cbranch_scc1 .Linv_dma_go
	s_mov_b32 s38, 0x26a00
	v_lshl_add_u32 v154, v148, 2, s38
	ds_read_b32 v150, v154
	ds_read_b32 v151, v154 offset:256
	ds_read_b32 v152, v154 offset:512
	ds_read_b32 v153, v154 offset:768
	ds_read_b32 v155, v154 offset:1024
	s_waitcnt lgkmcnt(0)
	v_readlane_b32 s64, v155, 0
	v_readlane_b32 s65, v155, 1
	v_readlane_b32 s66, v155, 2
	v_readlane_b32 s67, v155, 3
	v_readlane_b32 s68, v155, 4
	v_readlane_b32 s69, v155, 5
	v_readlane_b32 s70, v155, 6
	v_readlane_b32 s71, v155, 7
	v_readlane_b32 s44, v155, 8
	s_mov_b32 s45, 0
	s_mov_b64 s[14:15], 0x37f20000
	s_mov_b64 s[16:17], 0x37f24000
	s_mov_b64 s[18:19], 0x20000
	s_mov_b64 s[20:21], 0x24000
	s_mov_b64 s[22:23], 0x8020000
	s_mov_b64 s[24:25], 0x8024000
	s_mov_b64 s[26:27], 0xfa20000
	s_mov_b64 s[28:29], 0xfa24000
	s_mov_b64 s[30:31], 0x2000
	s_mov_b64 s[34:35], 0x4000
	s_mov_b64 s[40:41], 0x2205000
	s_mov_b64 s[46:47], 0x8000
	s_add_u32 s68, s68, s34
	s_addc_u32 s69, s69, s35
	s_mov_b32 s48, 5
	v_cmp_gt_u32_e64 s[42:43], 32, v148
.Linv_dma_go:
	s_mul_i32 s38, s48, 0xcccd
	s_lshr_b32 s38, s38, 18
	s_mul_i32 s38, s38, 5
	s_sub_i32 s38, s48, s38
	s_and_b32 s38, s38, 0xffff
	s_cmp_lg_u32 0, -1
	s_mulk_i32 s38, 0x2900
	s_cselect_b32 s39, 0, 0
	s_add_i32 s38, s39, s38
	s_add_i32 s36, s38, 0x19c00
	s_add_u32 s72, s64, s46
	s_addc_u32 s73, s65, s47
	s_add_u32 s76, s66, s46
	s_addc_u32 s77, s67, s47
	s_add_u32 s74, s72, s14
	s_addc_u32 s75, s73, s15
	s_mov_b32 m0, s36
	s_nop 0
	global_load_lds_dwordx4 v150, s[74:75]
	s_add_i32 s38, s36, 0x400
	s_add_u32 s74, s72, s16
	s_addc_u32 s75, s73, s17
	s_mov_b32 m0, s38
	s_nop 0
	global_load_lds_dwordx4 v150, s[74:75]
	s_add_i32 s38, s36, 0x800
	s_add_u32 s74, s76, s18
	s_addc_u32 s75, s77, s19
	s_mov_b32 m0, s38
	s_nop 0
	global_load_lds_dwordx4 v151, s[74:75]
	s_add_i32 s38, s36, 0xc00
	s_add_u32 s74, s76, s20
	s_addc_u32 s75, s77, s21
	s_mov_b32 m0, s38
	s_nop 0
	global_load_lds_dwordx4 v151, s[74:75]
	s_add_i32 s38, s36, 0x1000
	s_add_u32 s74, s76, s22
	s_addc_u32 s75, s77, s23
	s_mov_b32 m0, s38
	s_nop 0
	global_load_lds_dwordx4 v151, s[74:75]
	s_add_i32 s38, s36, 0x1400
	s_add_u32 s74, s76, s24
	s_addc_u32 s75, s77, s25
	s_mov_b32 m0, s38
	s_nop 0
	global_load_lds_dwordx4 v151, s[74:75]
	s_add_i32 s38, s36, 0x1800
	s_add_u32 s74, s72, s26
	s_addc_u32 s75, s73, s27
	s_mov_b32 m0, s38
	s_nop 0
	global_load_lds_dwordx4 v150, s[74:75]
	s_add_i32 s38, s36, 0x1c00
	s_add_u32 s74, s72, s28
	s_addc_u32 s75, s73, s29
	s_mov_b32 m0, s38
	s_nop 0
	global_load_lds_dwordx4 v150, s[74:75]
	s_and_saveexec_b64 s[50:51], s[42:43]
	s_cbranch_execz .Linv_dma_mid
	s_add_i32 s37, s36, 0x2000
	s_mov_b32 m0, s37
	s_nop 0
	global_load_lds_dwordx4 v152, s[68:69]
	s_add_i32 s37, s36, 0x2200
	s_add_u32 s74, s68, s30
	s_addc_u32 s75, s69, s31
	s_mov_b32 m0, s37
	s_nop 0
	global_load_lds_dwordx4 v152, s[74:75]
.Linv_dma_mid:
	s_or_b64 exec, exec, s[50:51]
	s_and_saveexec_b64 s[50:51], vcc
	s_cbranch_execz .Linv_dma_done
	s_add_u32 s74, s70, s40
	s_addc_u32 s75, s71, s41
	s_add_u32 s74, s74, s44
	s_addc_u32 s75, s75, s45
	s_addk_i32 s36, 0x2800
	s_mov_b32 m0, s36
	s_nop 0
	global_load_lds_dwordx4 v153, s[74:75]
.Linv_dma_done:
	s_or_b64 exec, exec, s[50:51]
	s_add_u32 s40, s40, 0x1000
	s_addc_u32 s41, s41, 0
	s_add_u32 s46, s46, 0x8000
	s_addc_u32 s47, s47, 0
	s_add_u32 s68, s68, s34
	s_addc_u32 s69, s69, s35
	s_add_i32 s48, s48, 1
